# swiglu units: leading half's ALIGN barrier moved after the epilogue preamble (tbl reads + address setup run during its wait)
# baseline (speedup 1.0000x reference)
; #define PG8_BAR __builtin_amdgcn_s_barrier()
; template <class Epi, class Sched, bool ALIGN_EPI = false, bool SP2 = false>
; __device__ __forceinline__ void gemm_phase(PG8_LAS unsigned char* lds, const Gemm g, const Sched& S, const Epi& E) {
;     ...
;         if constexpr (ALIGN_EPI) { if (wr == 0) PG8_BAR; }
;         if constexpr (!Epi::AFTER_DRAIN) { E(acc, cur, wr, wc, fr, fq, ui); S.done(cur); }
.LBB0_518:
	s_cmp_eq_u32 s88, 0
	s_cbranch_scc1 .LBB0_520
	v_readlane_b32 s2, v254, 34
	v_readlane_b32 s3, v254, 35
	s_and_b64 vcc, exec, s[2:3]
	s_cbranch_vccz .LBB0_520
	s_barrier

; #define PG8_BAR __builtin_amdgcn_s_barrier()
; #define LAS __attribute__((address_space(3)))
; __device__ __forceinline__ unsigned pk2(float lo, float hi) { f32x2 v = {lo, hi}; bf16x2_t b = __builtin_convertvector(v, bf16x2_t); return __builtin_bit_cast(unsigned, b); }
; template <class Epi, class Sched, bool ALIGN_EPI = false, bool SP2 = false>
; __device__ __forceinline__ void gemm_phase(PG8_LAS unsigned char* lds, const Gemm g, const Sched& S, const Epi& E) {
;     ...
;         if constexpr (ALIGN_EPI) { if (wr == 0) PG8_BAR; }
;         if constexpr (!Epi::AFTER_DRAIN) { E(acc, cur, wr, wc, fr, fq, ui); S.done(cur); }
; __device__ __forceinline__ void epi_swiglu(bf16_t* H, const LAS float* tbl, const f32x4 (&acc)[2][2][4][2], const Unit& u, int wr, int wc, int fr, int fq) {
;     const int col0 = u.pn * 128 + wc * 32 + fq * 8;
; #pragma unroll
;     for (int it = 0; it < 8; ++it) {
;         const int ai = it >> 2, m = it & 3; const int r = opaque(EPI_ROW(it));
;         const float rs = tbl[EPI_LROW(it)];
;         u32x4 w;
; #pragma unroll
;         for (int n = 0; n < 2; ++n) {
;             const f32x4 g = acc[ai][0][m][n] * rs, up = acc[ai][1][m][n] * rs; float hv[4];
; #pragma unroll
;             for (int i = 0; i < 4; ++i) hv[i] = g[i] * __builtin_amdgcn_rcpf(1.0f + __expf(-g[i])) * up[i];
;             w[2 * n] = pk2(hv[0], hv[1]); w[2 * n + 1] = pk2(hv[2], hv[3]);
;         }
;         *(u32x4*)(H + ((size_t)(r >> 8) * (DFF / 64) + (col0 >> 6)) * 16384 + (r & 255) * 64 + (col0 & 63)) = w;
;     }
.LBB0_752:
	s_and_b64 vcc, exec, s[2:3]
	s_cbranch_vccz .LBB0_754
	s_mov_b64 s[2:3], s[96:97]
	s_add_u32 s2, s2, 0x17e00000
	s_addc_u32 s3, s3, 0
	s_lshl_b32 s12, s77, 7
	v_readlane_b32 s13, v255, 1
	s_or_b32 s12, s12, s13
	v_readlane_b32 s13, v254, 31
	s_lshl_b32 s13, s13, 2
	s_add_i32 s39, s39, s13
	s_lshl_b32 s14, s81, 8
	s_waitcnt lgkmcnt(0)
	v_add_u32_e32 v131, s14, v193
	v_lshl_add_u32 v130, v183, 2, s39
	ds_read_b32 v140, v130
	ds_read_b32 v141, v130 offset:64
	ds_read_b32 v142, v130 offset:128
	ds_read_b32 v143, v130 offset:192
	ds_read_b32 v144, v130 offset:512
	ds_read_b32 v145, v130 offset:576
	ds_read_b32 v146, v130 offset:640
	ds_read_b32 v147, v130 offset:704
	s_ashr_i32 s12, s12, 6
	s_ashr_i32 s13, s12, 31
	v_mov_b32_e32 v199, v0
	v_lshrrev_b32_e32 v132, 8, v131
	v_mul_i32_i24_e32 v132, 0x58, v132
	v_ashrrev_i32_e32 v133, 31, v132
	v_lshl_add_u64 v[132:133], v[132:133], 0, s[12:13]
	v_lshlrev_b64 v[132:133], 15, v[132:133]
	v_lshl_add_u64 v[132:133], s[2:3], 0, v[132:133]
	v_lshlrev_b32_e32 v134, 7, v131
	v_and_b32_e32 v134, 0x7f80, v134
	v_mov_b32_e32 v135, v0
	v_lshl_add_u64 v[132:133], v[132:133], 0, v[134:135]
	v_lshl_add_u64 v[132:133], v[132:133], 0, v[198:199]
	s_mov_b64 s[12:13], 0x1000
	s_mov_b64 s[14:15], 0x5000
	v_lshl_add_u64 v[134:135], v[132:133], 0, s[12:13]
	v_lshl_add_u64 v[136:137], v[132:133], 0, s[14:15]
	v_mov_b32_e32 v138, 1.0
	v_mov_b32_e32 v139, 1.0
	s_waitcnt lgkmcnt(0)
	v_readlane_b32 s12, v254, 34
	v_readlane_b32 s13, v254, 35
	s_and_b64 vcc, exec, s[12:13]
	s_cbranch_vccz .Lsw_noalign
	s_barrier
.Lsw_noalign:
	v_mul_f32_e32 v148, 0xbfb8aa3b, v140
	v_mul_f32_e32 v150, v140, v140
	v_rcp_f32_e32 v150, v150
	v_pk_mul_f32 v[152:153], v[126:127], v[148:149] op_sel_hi:[1,0]
	v_pk_mul_f32 v[154:155], v[128:129], v[148:149] op_sel_hi:[1,0]
	v_pk_mul_f32 v[156:157], v[118:119], v[148:149] op_sel_hi:[1,0]
	v_pk_mul_f32 v[158:159], v[120:121], v[148:149] op_sel_hi:[1,0]
	v_exp_f32_e32 v152, v152
	v_exp_f32_e32 v153, v153
	v_exp_f32_e32 v154, v154
	v_exp_f32_e32 v155, v155
	v_exp_f32_e32 v156, v156
	v_exp_f32_e32 v157, v157
	v_exp_f32_e32 v158, v158
	v_exp_f32_e32 v159, v159
	v_pk_mul_f32 v[126:127], v[126:127], v[122:123]
	v_pk_mul_f32 v[128:129], v[128:129], v[124:125]
	v_pk_mul_f32 v[118:119], v[118:119], v[114:115]
	v_pk_mul_f32 v[120:121], v[120:121], v[116:117]
	v_pk_fma_f32 v[152:153], v[152:153], v[150:151], v[150:151] op_sel_hi:[1,0,0]
	v_pk_fma_f32 v[154:155], v[154:155], v[150:151], v[150:151] op_sel_hi:[1,0,0]
	v_pk_fma_f32 v[156:157], v[156:157], v[150:151], v[150:151] op_sel_hi:[1,0,0]
	v_pk_fma_f32 v[158:159], v[158:159], v[150:151], v[150:151] op_sel_hi:[1,0,0]
	v_rcp_f32_e32 v152, v152
	v_rcp_f32_e32 v153, v153
	v_rcp_f32_e32 v154, v154
	v_rcp_f32_e32 v155, v155
	v_rcp_f32_e32 v156, v156
	v_rcp_f32_e32 v157, v157
	v_rcp_f32_e32 v158, v158
	v_rcp_f32_e32 v159, v159
	v_pk_mul_f32 v[126:127], v[126:127], v[152:153]
	v_pk_mul_f32 v[128:129], v[128:129], v[154:155]
	v_pk_mul_f32 v[118:119], v[118:119], v[156:157]
	v_pk_mul_f32 v[120:121], v[120:121], v[158:159]
	v_cvt_pk_bf16_f32 v160, v126, v127
	v_cvt_pk_bf16_f32 v161, v128, v129
	v_cvt_pk_bf16_f32 v162, v118, v119
	v_cvt_pk_bf16_f32 v163, v120, v121
	global_store_dwordx4 v[134:135], v[160:163], off offset:-4096
	v_mul_f32_e32 v148, 0xbfb8aa3b, v141
	v_mul_f32_e32 v150, v141, v141
	v_rcp_f32_e32 v150, v150
	v_pk_mul_f32 v[152:153], v[110:111], v[148:149] op_sel_hi:[1,0]
	v_pk_mul_f32 v[154:155], v[112:113], v[148:149] op_sel_hi:[1,0]
	v_pk_mul_f32 v[156:157], v[102:103], v[148:149] op_sel_hi:[1,0]
	v_pk_mul_f32 v[158:159], v[104:105], v[148:149] op_sel_hi:[1,0]
	v_exp_f32_e32 v152, v152
	v_exp_f32_e32 v153, v153
	v_exp_f32_e32 v154, v154
	v_exp_f32_e32 v155, v155
	v_exp_f32_e32 v156, v156
	v_exp_f32_e32 v157, v157
	v_exp_f32_e32 v158, v158
	v_exp_f32_e32 v159, v159
	v_pk_mul_f32 v[110:111], v[110:111], v[106:107]
	v_pk_mul_f32 v[112:113], v[112:113], v[108:109]
	v_pk_mul_f32 v[102:103], v[102:103], v[98:99]
	v_pk_mul_f32 v[104:105], v[104:105], v[100:101]
	v_pk_fma_f32 v[152:153], v[152:153], v[150:151], v[150:151] op_sel_hi:[1,0,0]
	v_pk_fma_f32 v[154:155], v[154:155], v[150:151], v[150:151] op_sel_hi:[1,0,0]
	v_pk_fma_f32 v[156:157], v[156:157], v[150:151], v[150:151] op_sel_hi:[1,0,0]
	v_pk_fma_f32 v[158:159], v[158:159], v[150:151], v[150:151] op_sel_hi:[1,0,0]
	v_rcp_f32_e32 v152, v152
	v_rcp_f32_e32 v153, v153
	v_rcp_f32_e32 v154, v154
	v_rcp_f32_e32 v155, v155
	v_rcp_f32_e32 v156, v156
	v_rcp_f32_e32 v157, v157
	v_rcp_f32_e32 v158, v158
	v_rcp_f32_e32 v159, v159
	v_pk_mul_f32 v[110:111], v[110:111], v[152:153]
	v_pk_mul_f32 v[112:113], v[112:113], v[154:155]
	v_pk_mul_f32 v[102:103], v[102:103], v[156:157]
	v_pk_mul_f32 v[104:105], v[104:105], v[158:159]
	v_cvt_pk_bf16_f32 v164, v110, v111
	v_cvt_pk_bf16_f32 v165, v112, v113
	v_cvt_pk_bf16_f32 v166, v102, v103
	v_cvt_pk_bf16_f32 v167, v104, v105
	global_store_dwordx4 v[134:135], v[164:167], off offset:-2048
	v_mul_f32_e32 v148, 0xbfb8aa3b, v142
	v_mul_f32_e32 v150, v142, v142
	v_rcp_f32_e32 v150, v150
	v_pk_mul_f32 v[152:153], v[94:95], v[148:149] op_sel_hi:[1,0]
	v_pk_mul_f32 v[154:155], v[96:97], v[148:149] op_sel_hi:[1,0]
	v_pk_mul_f32 v[156:157], v[86:87], v[148:149] op_sel_hi:[1,0]
	v_pk_mul_f32 v[158:159], v[88:89], v[148:149] op_sel_hi:[1,0]
	v_exp_f32_e32 v152, v152
	v_exp_f32_e32 v153, v153
	v_exp_f32_e32 v154, v154
	v_exp_f32_e32 v155, v155
	v_exp_f32_e32 v156, v156
	v_exp_f32_e32 v157, v157
	v_exp_f32_e32 v158, v158
	v_exp_f32_e32 v159, v159
	v_pk_mul_f32 v[94:95], v[94:95], v[90:91]
	v_pk_mul_f32 v[96:97], v[96:97], v[92:93]
	v_pk_mul_f32 v[86:87], v[86:87], v[82:83]
; __device__ __forceinline__ unsigned pk2(float lo, float hi) { f32x2 v = {lo, hi}; bf16x2_t b = __builtin_convertvector(v, bf16x2_t); return __builtin_bit_cast(unsigned, b); }
; __device__ __forceinline__ void epi_swiglu(bf16_t* H, const LAS float* tbl, const f32x4 (&acc)[2][2][4][2], const Unit& u, int wr, int wc, int fr, int fq) {
;     ...
;     for (int it = 0; it < 8; ++it) {
;         const int ai = it >> 2, m = it & 3; const int r = opaque(EPI_ROW(it));
;         const float rs = tbl[EPI_LROW(it)];
;         u32x4 w;
; #pragma unroll
;         for (int n = 0; n < 2; ++n) {
;             const f32x4 g = acc[ai][0][m][n] * rs, up = acc[ai][1][m][n] * rs; float hv[4];
; #pragma unroll
;             for (int i = 0; i < 4; ++i) hv[i] = g[i] * __builtin_amdgcn_rcpf(1.0f + __expf(-g[i])) * up[i];
;             w[2 * n] = pk2(hv[0], hv[1]); w[2 * n + 1] = pk2(hv[2], hv[3]);
;         }
;         *(u32x4*)(H + ((size_t)(r >> 8) * (DFF / 64) + (col0 >> 6)) * 16384 + (r & 255) * 64 + (col0 & 63)) = w;
;     }
	v_pk_mul_f32 v[88:89], v[88:89], v[84:85]
	v_pk_fma_f32 v[152:153], v[152:153], v[150:151], v[150:151] op_sel_hi:[1,0,0]
	v_pk_fma_f32 v[154:155], v[154:155], v[150:151], v[150:151] op_sel_hi:[1,0,0]
	v_pk_fma_f32 v[156:157], v[156:157], v[150:151], v[150:151] op_sel_hi:[1,0,0]
	v_pk_fma_f32 v[158:159], v[158:159], v[150:151], v[150:151] op_sel_hi:[1,0,0]
	v_rcp_f32_e32 v152, v152
	v_rcp_f32_e32 v153, v153
	v_rcp_f32_e32 v154, v154
	v_rcp_f32_e32 v155, v155
	v_rcp_f32_e32 v156, v156
	v_rcp_f32_e32 v157, v157
	v_rcp_f32_e32 v158, v158
	v_rcp_f32_e32 v159, v159
	v_pk_mul_f32 v[94:95], v[94:95], v[152:153]
	v_pk_mul_f32 v[96:97], v[96:97], v[154:155]
	v_pk_mul_f32 v[86:87], v[86:87], v[156:157]
	v_pk_mul_f32 v[88:89], v[88:89], v[158:159]
	v_cvt_pk_bf16_f32 v160, v94, v95
	v_cvt_pk_bf16_f32 v161, v96, v97
	v_cvt_pk_bf16_f32 v162, v86, v87
	v_cvt_pk_bf16_f32 v163, v88, v89
	global_store_dwordx4 v[134:135], v[160:163], off
	v_mul_f32_e32 v148, 0xbfb8aa3b, v143
	v_mul_f32_e32 v150, v143, v143
	v_rcp_f32_e32 v150, v150
	v_pk_mul_f32 v[152:153], v[78:79], v[148:149] op_sel_hi:[1,0]
	v_pk_mul_f32 v[154:155], v[80:81], v[148:149] op_sel_hi:[1,0]
	v_pk_mul_f32 v[156:157], v[70:71], v[148:149] op_sel_hi:[1,0]
	v_pk_mul_f32 v[158:159], v[72:73], v[148:149] op_sel_hi:[1,0]
	v_exp_f32_e32 v152, v152
	v_exp_f32_e32 v153, v153
	v_exp_f32_e32 v154, v154
	v_exp_f32_e32 v155, v155
	v_exp_f32_e32 v156, v156
	v_exp_f32_e32 v157, v157
	v_exp_f32_e32 v158, v158
	v_exp_f32_e32 v159, v159
	v_pk_mul_f32 v[78:79], v[78:79], v[74:75]
	v_pk_mul_f32 v[80:81], v[80:81], v[76:77]
	v_pk_mul_f32 v[70:71], v[70:71], v[66:67]
	v_pk_mul_f32 v[72:73], v[72:73], v[68:69]
	v_pk_fma_f32 v[152:153], v[152:153], v[150:151], v[150:151] op_sel_hi:[1,0,0]
	v_pk_fma_f32 v[154:155], v[154:155], v[150:151], v[150:151] op_sel_hi:[1,0,0]
	v_pk_fma_f32 v[156:157], v[156:157], v[150:151], v[150:151] op_sel_hi:[1,0,0]
	v_pk_fma_f32 v[158:159], v[158:159], v[150:151], v[150:151] op_sel_hi:[1,0,0]
	v_rcp_f32_e32 v152, v152
	v_rcp_f32_e32 v153, v153
	v_rcp_f32_e32 v154, v154
	v_rcp_f32_e32 v155, v155
	v_rcp_f32_e32 v156, v156
	v_rcp_f32_e32 v157, v157
	v_rcp_f32_e32 v158, v158
	v_rcp_f32_e32 v159, v159
	v_pk_mul_f32 v[78:79], v[78:79], v[152:153]
	v_pk_mul_f32 v[80:81], v[80:81], v[154:155]
	v_pk_mul_f32 v[70:71], v[70:71], v[156:157]
	v_pk_mul_f32 v[72:73], v[72:73], v[158:159]
	v_cvt_pk_bf16_f32 v164, v78, v79
	v_cvt_pk_bf16_f32 v165, v80, v81
	v_cvt_pk_bf16_f32 v166, v70, v71
	v_cvt_pk_bf16_f32 v167, v72, v73
	global_store_dwordx4 v[134:135], v[164:167], off offset:2048
	v_mul_f32_e32 v148, 0xbfb8aa3b, v144
	v_mul_f32_e32 v150, v144, v144
	v_rcp_f32_e32 v150, v150
	v_pk_mul_f32 v[152:153], v[62:63], v[148:149] op_sel_hi:[1,0]
	v_pk_mul_f32 v[154:155], v[64:65], v[148:149] op_sel_hi:[1,0]
	v_pk_mul_f32 v[156:157], v[54:55], v[148:149] op_sel_hi:[1,0]
	v_pk_mul_f32 v[158:159], v[56:57], v[148:149] op_sel_hi:[1,0]
	v_exp_f32_e32 v152, v152
	v_exp_f32_e32 v153, v153
	v_exp_f32_e32 v154, v154
	v_exp_f32_e32 v155, v155
	v_exp_f32_e32 v156, v156
	v_exp_f32_e32 v157, v157
	v_exp_f32_e32 v158, v158
	v_exp_f32_e32 v159, v159
	v_pk_mul_f32 v[62:63], v[62:63], v[58:59]
	v_pk_mul_f32 v[64:65], v[64:65], v[60:61]
	v_pk_mul_f32 v[54:55], v[54:55], v[50:51]
	v_pk_mul_f32 v[56:57], v[56:57], v[52:53]
	v_pk_fma_f32 v[152:153], v[152:153], v[150:151], v[150:151] op_sel_hi:[1,0,0]
	v_pk_fma_f32 v[154:155], v[154:155], v[150:151], v[150:151] op_sel_hi:[1,0,0]
	v_pk_fma_f32 v[156:157], v[156:157], v[150:151], v[150:151] op_sel_hi:[1,0,0]
	v_pk_fma_f32 v[158:159], v[158:159], v[150:151], v[150:151] op_sel_hi:[1,0,0]
	v_rcp_f32_e32 v152, v152
	v_rcp_f32_e32 v153, v153
	v_rcp_f32_e32 v154, v154
	v_rcp_f32_e32 v155, v155
	v_rcp_f32_e32 v156, v156
	v_rcp_f32_e32 v157, v157
	v_rcp_f32_e32 v158, v158
	v_rcp_f32_e32 v159, v159
	v_pk_mul_f32 v[62:63], v[62:63], v[152:153]
	v_pk_mul_f32 v[64:65], v[64:65], v[154:155]
	v_pk_mul_f32 v[54:55], v[54:55], v[156:157]
	v_pk_mul_f32 v[56:57], v[56:57], v[158:159]
	v_cvt_pk_bf16_f32 v160, v62, v63
	v_cvt_pk_bf16_f32 v161, v64, v65
	v_cvt_pk_bf16_f32 v162, v54, v55
	v_cvt_pk_bf16_f32 v163, v56, v57
	global_store_dwordx4 v[136:137], v[160:163], off offset:-4096
	v_mul_f32_e32 v148, 0xbfb8aa3b, v145
	v_mul_f32_e32 v150, v145, v145
	v_rcp_f32_e32 v150, v150
	v_pk_mul_f32 v[152:153], v[46:47], v[148:149] op_sel_hi:[1,0]
	v_pk_mul_f32 v[154:155], v[48:49], v[148:149] op_sel_hi:[1,0]
	v_pk_mul_f32 v[156:157], v[38:39], v[148:149] op_sel_hi:[1,0]
	v_pk_mul_f32 v[158:159], v[40:41], v[148:149] op_sel_hi:[1,0]
; __device__ __forceinline__ unsigned pk2(float lo, float hi) { f32x2 v = {lo, hi}; bf16x2_t b = __builtin_convertvector(v, bf16x2_t); return __builtin_bit_cast(unsigned, b); }
; __device__ __forceinline__ void epi_swiglu(bf16_t* H, const LAS float* tbl, const f32x4 (&acc)[2][2][4][2], const Unit& u, int wr, int wc, int fr, int fq) {
;     ...
;     for (int it = 0; it < 8; ++it) {
;         const int ai = it >> 2, m = it & 3; const int r = opaque(EPI_ROW(it));
;         const float rs = tbl[EPI_LROW(it)];
;         u32x4 w;
; #pragma unroll
;         for (int n = 0; n < 2; ++n) {
;             const f32x4 g = acc[ai][0][m][n] * rs, up = acc[ai][1][m][n] * rs; float hv[4];
; #pragma unroll
;             for (int i = 0; i < 4; ++i) hv[i] = g[i] * __builtin_amdgcn_rcpf(1.0f + __expf(-g[i])) * up[i];
;             w[2 * n] = pk2(hv[0], hv[1]); w[2 * n + 1] = pk2(hv[2], hv[3]);
;         }
;         *(u32x4*)(H + ((size_t)(r >> 8) * (DFF / 64) + (col0 >> 6)) * 16384 + (r & 255) * 64 + (col0 & 63)) = w;
;     }
	v_exp_f32_e32 v152, v152
	v_exp_f32_e32 v153, v153
	v_exp_f32_e32 v154, v154
	v_exp_f32_e32 v155, v155
	v_exp_f32_e32 v156, v156
	v_exp_f32_e32 v157, v157
	v_exp_f32_e32 v158, v158
	v_exp_f32_e32 v159, v159
	v_pk_mul_f32 v[46:47], v[46:47], v[42:43]
	v_pk_mul_f32 v[48:49], v[48:49], v[44:45]
	v_pk_mul_f32 v[38:39], v[38:39], v[34:35]
	v_pk_mul_f32 v[40:41], v[40:41], v[36:37]
	v_pk_fma_f32 v[152:153], v[152:153], v[150:151], v[150:151] op_sel_hi:[1,0,0]
	v_pk_fma_f32 v[154:155], v[154:155], v[150:151], v[150:151] op_sel_hi:[1,0,0]
	v_pk_fma_f32 v[156:157], v[156:157], v[150:151], v[150:151] op_sel_hi:[1,0,0]
	v_pk_fma_f32 v[158:159], v[158:159], v[150:151], v[150:151] op_sel_hi:[1,0,0]
	v_rcp_f32_e32 v152, v152
	v_rcp_f32_e32 v153, v153
	v_rcp_f32_e32 v154, v154
	v_rcp_f32_e32 v155, v155
	v_rcp_f32_e32 v156, v156
	v_rcp_f32_e32 v157, v157
	v_rcp_f32_e32 v158, v158
	v_rcp_f32_e32 v159, v159
	v_pk_mul_f32 v[46:47], v[46:47], v[152:153]
	v_pk_mul_f32 v[48:49], v[48:49], v[154:155]
	v_pk_mul_f32 v[38:39], v[38:39], v[156:157]
	v_pk_mul_f32 v[40:41], v[40:41], v[158:159]
	v_cvt_pk_bf16_f32 v164, v46, v47
	v_cvt_pk_bf16_f32 v165, v48, v49
	v_cvt_pk_bf16_f32 v166, v38, v39
	v_cvt_pk_bf16_f32 v167, v40, v41
	global_store_dwordx4 v[136:137], v[164:167], off offset:-2048
	v_mul_f32_e32 v148, 0xbfb8aa3b, v146
	v_mul_f32_e32 v150, v146, v146
	v_rcp_f32_e32 v150, v150
	v_pk_mul_f32 v[152:153], v[30:31], v[148:149] op_sel_hi:[1,0]
	v_pk_mul_f32 v[154:155], v[32:33], v[148:149] op_sel_hi:[1,0]
	v_pk_mul_f32 v[156:157], v[22:23], v[148:149] op_sel_hi:[1,0]
	v_pk_mul_f32 v[158:159], v[24:25], v[148:149] op_sel_hi:[1,0]
	v_exp_f32_e32 v152, v152
	v_exp_f32_e32 v153, v153
	v_exp_f32_e32 v154, v154
	v_exp_f32_e32 v155, v155
	v_exp_f32_e32 v156, v156
	v_exp_f32_e32 v157, v157
	v_exp_f32_e32 v158, v158
	v_exp_f32_e32 v159, v159
	v_pk_mul_f32 v[30:31], v[30:31], v[26:27]
	v_pk_mul_f32 v[32:33], v[32:33], v[28:29]
	v_pk_mul_f32 v[22:23], v[22:23], v[18:19]
	v_pk_mul_f32 v[24:25], v[24:25], v[20:21]
	v_pk_fma_f32 v[152:153], v[152:153], v[150:151], v[150:151] op_sel_hi:[1,0,0]
	v_pk_fma_f32 v[154:155], v[154:155], v[150:151], v[150:151] op_sel_hi:[1,0,0]
	v_pk_fma_f32 v[156:157], v[156:157], v[150:151], v[150:151] op_sel_hi:[1,0,0]
	v_pk_fma_f32 v[158:159], v[158:159], v[150:151], v[150:151] op_sel_hi:[1,0,0]
	v_rcp_f32_e32 v152, v152
	v_rcp_f32_e32 v153, v153
	v_rcp_f32_e32 v154, v154
	v_rcp_f32_e32 v155, v155
	v_rcp_f32_e32 v156, v156
	v_rcp_f32_e32 v157, v157
	v_rcp_f32_e32 v158, v158
	v_rcp_f32_e32 v159, v159
	v_pk_mul_f32 v[30:31], v[30:31], v[152:153]
	v_pk_mul_f32 v[32:33], v[32:33], v[154:155]
	v_pk_mul_f32 v[22:23], v[22:23], v[156:157]
	v_pk_mul_f32 v[24:25], v[24:25], v[158:159]
	v_cvt_pk_bf16_f32 v160, v30, v31
	v_cvt_pk_bf16_f32 v161, v32, v33
	v_cvt_pk_bf16_f32 v162, v22, v23
	v_cvt_pk_bf16_f32 v163, v24, v25
	global_store_dwordx4 v[136:137], v[160:163], off
	v_mul_f32_e32 v148, 0xbfb8aa3b, v147
	v_mul_f32_e32 v150, v147, v147
	v_rcp_f32_e32 v150, v150
	v_pk_mul_f32 v[152:153], v[14:15], v[148:149] op_sel_hi:[1,0]
	v_pk_mul_f32 v[154:155], v[16:17], v[148:149] op_sel_hi:[1,0]
	v_pk_mul_f32 v[156:157], v[6:7], v[148:149] op_sel_hi:[1,0]
	v_pk_mul_f32 v[158:159], v[8:9], v[148:149] op_sel_hi:[1,0]
	v_exp_f32_e32 v152, v152
	v_exp_f32_e32 v153, v153
	v_exp_f32_e32 v154, v154
	v_exp_f32_e32 v155, v155
	v_exp_f32_e32 v156, v156
	v_exp_f32_e32 v157, v157
	v_exp_f32_e32 v158, v158
	v_exp_f32_e32 v159, v159
	v_pk_mul_f32 v[14:15], v[14:15], v[10:11]
	v_pk_mul_f32 v[16:17], v[16:17], v[12:13]
	v_pk_mul_f32 v[6:7], v[6:7], v[2:3]
	v_pk_mul_f32 v[8:9], v[8:9], v[4:5]
	v_pk_fma_f32 v[152:153], v[152:153], v[150:151], v[150:151] op_sel_hi:[1,0,0]
	v_pk_fma_f32 v[154:155], v[154:155], v[150:151], v[150:151] op_sel_hi:[1,0,0]
	v_pk_fma_f32 v[156:157], v[156:157], v[150:151], v[150:151] op_sel_hi:[1,0,0]
	v_pk_fma_f32 v[158:159], v[158:159], v[150:151], v[150:151] op_sel_hi:[1,0,0]
	v_rcp_f32_e32 v152, v152
	v_rcp_f32_e32 v153, v153
	v_rcp_f32_e32 v154, v154
	v_rcp_f32_e32 v155, v155
	v_rcp_f32_e32 v156, v156
	v_rcp_f32_e32 v157, v157
	v_rcp_f32_e32 v158, v158
	v_rcp_f32_e32 v159, v159
	v_pk_mul_f32 v[14:15], v[14:15], v[152:153]
	v_pk_mul_f32 v[16:17], v[16:17], v[154:155]
	v_pk_mul_f32 v[6:7], v[6:7], v[156:157]
	v_pk_mul_f32 v[8:9], v[8:9], v[158:159]
	v_cvt_pk_bf16_f32 v164, v14, v15
	v_cvt_pk_bf16_f32 v165, v16, v17
	v_cvt_pk_bf16_f32 v166, v6, v7
	v_cvt_pk_bf16_f32 v167, v8, v9
	global_store_dwordx4 v[136:137], v[164:167], off offset:2048
